# attention rescale: 16 packed v_pk_mul_f32 on the O accumulators split into scalar v_mul_f32 pairs (bit-identical)
# speedup vs baseline: 1.0104x; 1.0104x over previous
; __device__ __forceinline__ void attn_phase(const Ctx& c, const Params& p, int o, int first, int cidx) {
;     ...
;                 float mxa = fmaxf(fmaxf(p0[0], p1[0]), p0[1]), mxb = fmaxf(fmaxf(p1[1], p0[2]), p1[2]);
; #pragma unroll
;                 for (int r = 3; r < 15; r += 2) { mxa = fmaxf(fmaxf(mxa, p0[r]), p1[r]); mxb = fmaxf(fmaxf(mxb, p0[r + 1]), p1[r + 1]); }
;                 float mx = fmaxf(fmaxf(mxa, mxb), fmaxf(p0[15], p1[15]));
;                 { auto rr = __builtin_amdgcn_permlane32_swap(asu(mx), asu(mx), false, false); mx = fmaxf(asf(rr[0]), asf(rr[1])); }
;                 const float mnew = fmaxf(mrun, mx);
;                 if (__any(mnew > mrun)) { const float alpha = __builtin_amdgcn_exp2f(mrun - mnew); lrun *= alpha; o0 = o0 * alpha; o1 = o1 * alpha; }
;                 mrun = mnew;
.LBB0_127:
	s_nop 10
	v_max3_f32 v1, v50, v34, v51
	v_max3_f32 v138, v35, v52, v36
	v_max3_f32 v1, v1, v53, v37
	v_max3_f32 v138, v138, v54, v38
	v_max3_f32 v1, v1, v55, v39
	v_max3_f32 v138, v138, v56, v40
	v_max3_f32 v1, v1, v57, v41
	v_max3_f32 v138, v138, v58, v42
	v_max3_f32 v1, v1, v59, v43
	v_max3_f32 v138, v138, v60, v44
	v_max3_f32 v1, v1, v61, v45
	v_max3_f32 v138, v138, v62, v46
	v_max_f32_e32 v139, v49, v49
	v_max_f32_e32 v140, v65, v65
	v_max3_f32 v1, v1, v63, v47
	v_max3_f32 v138, v138, v64, v48
	v_max_f32_e32 v139, v140, v139
	v_max3_f32 v1, v1, v138, v139
	v_mov_b32_e32 v138, v1
	s_nop 1
	v_permlane32_swap_b32_e32 v1, v138
	v_max3_f32 v1, v137, v1, v138
	v_cmp_gt_f32_e32 vcc, v1, v137
	s_cbranch_vccz .LBB0_129
	v_sub_f32_e32 v137, v137, v1
	v_exp_f32_e32 v138, v137
	s_nop 0
	v_mul_f32_e32 v136, v136, v138
	v_mul_f32_e32 v32, v138, v32
	v_mul_f32_e32 v33, v138, v33
	v_mul_f32_e32 v30, v138, v30
	v_mul_f32_e32 v31, v138, v31
	v_mul_f32_e32 v28, v138, v28
	v_mul_f32_e32 v29, v138, v29
	v_mul_f32_e32 v26, v138, v26
	v_mul_f32_e32 v27, v138, v27
	v_mul_f32_e32 v24, v138, v24
	v_mul_f32_e32 v25, v138, v25
	v_mul_f32_e32 v22, v138, v22
	v_mul_f32_e32 v23, v138, v23
	v_mul_f32_e32 v20, v138, v20
	v_mul_f32_e32 v21, v138, v21
	v_mul_f32_e32 v18, v138, v18
	v_mul_f32_e32 v19, v138, v19
	v_mul_f32_e32 v16, v138, v16
	v_mul_f32_e32 v17, v138, v17
	v_mul_f32_e32 v14, v138, v14
	v_mul_f32_e32 v15, v138, v15
	v_mul_f32_e32 v12, v138, v12
	v_mul_f32_e32 v13, v138, v13
	v_mul_f32_e32 v10, v138, v10
	v_mul_f32_e32 v11, v138, v11
	v_mul_f32_e32 v8, v138, v8
	v_mul_f32_e32 v9, v138, v9
	v_mul_f32_e32 v6, v138, v6
	v_mul_f32_e32 v7, v138, v7
	v_mul_f32_e32 v4, v138, v4
	v_mul_f32_e32 v5, v138, v5
	v_mul_f32_e32 v2, v138, v2
	v_mul_f32_e32 v3, v138, v3
